# barrier elision: G3 unit loop drops the pre-staging barrier (previous unit's LDS reads all precede its row-sum-exchange barrier)
# baseline (speedup 1.0000x reference)
; #define LAS __attribute__((address_space(3)))
; #define GLA_BAR() do { asm volatile("s_waitcnt lgkmcnt(0)" ::: "memory"); __builtin_amdgcn_s_barrier(); asm volatile("" ::: "memory"); } while (0)
; __device__ __forceinline__ void ph_g3(Frame& F, int e, int nrc) {
;     ...
;     for (; u < nrc * 8; u += F.G) {
;         const int rc = u >> 3, h = u & 7;
;         GLA_BAR();
;         { LAS unsigned* dst = (LAS unsigned*)(VT + s_d8 * PITCH + s_tp);
;             dst[0 * (PITCH / 2)] = (pv0.x & 0xffffu) | (pv1.x << 16); dst[1 * (PITCH / 2)] = (pv0.x >> 16) | (pv1.x & 0xffff0000u);
;             dst[2 * (PITCH / 2)] = (pv0.y & 0xffffu) | (pv1.y << 16); dst[3 * (PITCH / 2)] = (pv0.y >> 16) | (pv1.y & 0xffff0000u);
;             dst[4 * (PITCH / 2)] = (pv0.z & 0xffffu) | (pv1.z << 16); dst[5 * (PITCH / 2)] = (pv0.z >> 16) | (pv1.z & 0xffff0000u);
;             dst[6 * (PITCH / 2)] = (pv0.w & 0xffffu) | (pv1.w << 16); dst[7 * (PITCH / 2)] = (pv0.w >> 16) | (pv1.w & 0xffff0000u);
;             const int lo = s_t * PITCH + s_c8;
;             *(LAS v4u*)(QFl + lo) = pqf; *(LAS v4u*)(KFl + lo) = pkf; *(LAS v4u*)(QBl + lo) = pqb; *(LAS v4u*)(KBl + lo) = pkb; }
;         bf16x8 sf[4], sb[4];
; #pragma unroll
;         for (int ks = 0; ks < 4; ++ks) { sf[ks] = nsf[ks]; sb[ks] = nsb[ks]; }
;         GLA_BAR();
;         if (u + F.G < nrc * 8) G3_LOAD(u + F.G);
.LBB0_997:
	v_and_b32_e32 v24, 0xffff, v52
	v_lshrrev_b32_e32 v25, 16, v52
	s_mov_b32 s8, 0xffff0000
	v_lshl_or_b32 v24, v56, 16, v24
	v_and_or_b32 v25, v56, s8, v25
	s_waitcnt lgkmcnt(0)
	ds_write2_b32 v153, v24, v25 offset1:36
	v_and_b32_e32 v24, 0xffff, v53
	v_lshrrev_b32_e32 v25, 16, v53
	v_lshl_or_b32 v24, v57, 16, v24
	v_and_or_b32 v25, v57, s8, v25
	ds_write2_b32 v153, v24, v25 offset0:72 offset1:108
	v_and_b32_e32 v24, 0xffff, v54
	v_lshrrev_b32_e32 v25, 16, v54
	v_lshl_or_b32 v24, v58, 16, v24
	v_and_or_b32 v25, v58, s8, v25
	ds_write2_b32 v153, v24, v25 offset0:144 offset1:180
	v_and_b32_e32 v24, 0xffff, v55
	v_lshrrev_b32_e32 v25, 16, v55
	v_lshl_or_b32 v24, v59, 16, v24
	v_and_or_b32 v25, v59, s8, v25
	v_readlane_b32 s8, v253, 4
	ds_write2_b32 v153, v24, v25 offset0:216 offset1:252
	ds_write_b128 v143, v[60:63] offset:18432
	ds_write_b128 v143, v[64:67] offset:27648
	ds_write_b128 v143, v[68:71] offset:36864
	ds_write_b128 v143, v[72:75] offset:46080
	s_add_i32 s8, s9, s8
	s_waitcnt lgkmcnt(0)
	s_barrier
	s_ashr_i32 s32, s9, 3
	s_lshl_b32 s32, s32, 6
	v_or_b32_e32 v180, s32, v142
	v_mov_b64_e32 v[182:183], s[12:13]
	s_movk_i32 s99, 0x3200
	v_mad_u64_u32 v[182:183], vcc, v180, s99, v[182:183]
	s_and_b32 s32, s21, 0x380
	s_lshl_b32 s99, s32, 1
	s_addk_i32 s99, 0x2800
	s_lshl_b32 s32, s32, 2
	v_add_co_u32_e32 v182, vcc, s99, v182
	s_nop 1
	v_addc_co_u32_e32 v183, vcc, 0, v183, vcc
	v_lshl_add_u64 v[182:183], v[182:183], 0, v[146:147]
	v_add_co_u32_e32 v186, vcc, s32, v144
	s_nop 1
	v_addc_co_u32_e32 v187, vcc, 0, v145, vcc
	global_load_dwordx2 v[188:189], v[182:183], off
	global_load_dwordx4 v[190:193], v[186:187], off
	global_load_dwordx2 v[194:195], v[182:183], off offset:16
	global_load_dwordx4 v[196:199], v[186:187], off offset:32
	global_load_dwordx2 v[200:201], v[182:183], off offset:32
	global_load_dwordx4 v[202:205], v[186:187], off offset:64
	global_load_dwordx2 v[206:207], v[182:183], off offset:48
	global_load_dwordx4 v[208:211], v[186:187], off offset:96
	s_cmp_ge_i32 s8, s20
	s_cselect_b64 s[10:11], -1, 0
	s_and_b64 vcc, exec, s[10:11]
	s_cbranch_vccnz .LBB0_999
	s_ashr_i32 s18, s8, 3
	s_and_b32 s19, s18, 63
	s_and_b32 s30, s18, 3
	s_sub_i32 vcc_lo, 0x43, s19
	s_xor_b32 vcc_hi, s30, 3
	s_cmpk_lt_i32 s18, 0x100
	s_cselect_b32 s27, vcc_lo, vcc_hi
	s_add_i32 s19, s19, 4
	s_cmpk_lt_i32 s18, 0x100
	s_cselect_b32 s30, s19, s30
	s_add_i32 vcc_lo, s18, 0x3fffff00
	s_ashr_i32 s19, s8, 9
	s_lshr_b32 vcc_lo, vcc_lo, 2
	s_cmpk_lt_i32 s18, 0x100
	s_cselect_b32 s28, s19, vcc_lo
	s_and_b32 s17, s8, 7
	s_ashr_i32 s19, s18, 31
	s_mul_i32 vcc_hi, s18, 0xc8000
	s_mul_hi_i32 vcc_lo, s18, 0xc8000
	s_add_u32 vcc_hi, s12, vcc_hi
	s_addc_u32 s15, s13, vcc_lo
	s_lshl_b32 s16, s17, 7
	s_lshl_b32 vcc_lo, s17, 8
	s_add_u32 vcc_lo, vcc_hi, vcc_lo
	s_addc_u32 vcc_hi, s15, 0
	v_lshl_add_u64 v[24:25], v[2:3], 1, vcc
	v_add_co_u32_e32 v26, vcc, s3, v24
	s_movk_i32 s2, 0x5000
	s_nop 0
	v_addc_co_u32_e32 v27, vcc, 0, v25, vcc
	s_lshl_b64 s[18:19], s[18:19], 16
	v_add_co_u32_e32 v24, vcc, s2, v24
	s_or_b32 s18, s18, s16
	s_lshl_b32 s15, s28, 4
	s_lshl_b32 s16, s17, 1
	v_addc_co_u32_e32 v25, vcc, 0, v25, vcc
	s_or_b32 s15, s15, s16
	global_load_dwordx4 v[52:55], v[26:27], off
	global_load_dwordx4 v[56:59], v[24:25], off offset:512
	v_lshl_add_u64 v[24:25], v[132:133], 0, s[18:19]
	v_lshl_add_u64 v[26:27], v[134:135], 0, s[18:19]
	s_mul_i32 s17, s15, 0x44
	global_load_dwordx4 v[60:63], v[24:25], off
	global_load_dwordx4 v[64:67], v[26:27], off
	v_lshl_add_u64 v[24:25], v[136:137], 0, s[18:19]
	v_lshl_add_u64 v[26:27], v[138:139], 0, s[18:19]
	s_mul_hi_i32 s16, s15, 0x44
	s_add_u32 s18, s17, s30
	s_addc_u32 s19, s16, 0
	s_or_b32 s15, s15, 1
	s_lshl_b64 s[18:19], s[18:19], 14
	s_mul_hi_i32 s16, s15, 0x44
	s_mulk_i32 s15, 0x44
	s_add_u32 vcc_lo, s15, s27
	s_addc_u32 vcc_hi, s16, 0
	global_load_dwordx4 v[68:71], v[24:25], off
	global_load_dwordx4 v[72:75], v[26:27], off
	s_lshl_b64 vcc, vcc, 14
	v_lshl_add_u64 v[24:25], v[140:141], 0, s[18:19]
	v_lshl_add_u64 v[26:27], v[140:141], 0, vcc
	global_load_dwordx4 v[76:79], v[24:25], off
	global_load_dwordx4 v[88:91], v[24:25], off offset:32
	global_load_dwordx4 v[84:87], v[26:27], off
	global_load_dwordx4 v[80:83], v[26:27], off offset:32
	global_load_dwordx4 v[100:103], v[24:25], off offset:64
	global_load_dwordx4 v[104:107], v[24:25], off offset:96
	global_load_dwordx4 v[96:99], v[26:27], off offset:64
	global_load_dwordx4 v[92:95], v[26:27], off offset:96
	v_readlane_b32 s28, v255, 17
	v_readlane_b32 s27, v255, 16
	v_readlane_b32 s2, v253, 9
	v_readlane_b32 s16, v255, 14
	v_readlane_b32 s17, v255, 15
